# barrier 5 first pass: WGs 0-127 only arrive (no wait) before their fifth in-proj unit
# baseline (speedup 1.0000x reference)
; __device__ __forceinline__ unsigned xb_ld(unsigned* p)              { return __hip_atomic_load(p, __ATOMIC_RELAXED, __HIP_MEMORY_SCOPE_AGENT); }
; __device__ __forceinline__ unsigned xb_add(unsigned* p, unsigned v) { return __hip_atomic_fetch_add(p, v, __ATOMIC_RELAXED, __HIP_MEMORY_SCOPE_AGENT); }
; #define XB_SPIN(cond, bar) do { unsigned _sp = 0; while (cond) { __builtin_amdgcn_s_sleep(1); \
;     if ((++_sp & 255u) == 0u) { if (xb_ld(&(bar)[XB_TMO])) break; if (_sp > XB_SPIN_CAP) { atomicAdd(&(bar)[XB_TMO], 1u); break; } } } } while (0)
; __device__ __forceinline__ void xcd_barrier(const XcdBarrier& b) {
;     ...
;         const unsigned old = xb_add(&bar[XB_XSUB(b.x)], 1u);
;         const unsigned gen = old / nloc;
;         if (old + 1u == (gen + 1u) * nloc) {
;             __builtin_amdgcn_fence(__ATOMIC_RELEASE, "agent");
;             asm volatile("s_waitcnt vmcnt(0)" ::: "memory");
;             const unsigned og = xb_add(&bar[XB_TOP], 1u);
;             const unsigned tg = og / nx;
;             if (og + 1u == (tg + 1u) * nx) xb_add(&bar[XB_TOPGEN], 1u);
;             else XB_SPIN(xb_ld(&bar[XB_TOPGEN]) == tg, bar);
;             __builtin_amdgcn_fence(__ATOMIC_ACQUIRE, "agent");
;             xb_add(&bar[XB_XGEN(b.x)], 1u);
;             asm volatile("s_waitcnt vmcnt(0)" ::: "memory");
;         } else {
;             XB_SPIN(xb_ld(&bar[XB_XGEN(b.x)]) == gen, bar);
.LBB0_873:
	s_or_b64 exec, exec, s[8:9]
	v_cvt_f32_u32_e32 v4, v2
	s_waitcnt vmcnt(0)
	v_readfirstlane_b32 s2, v3
	v_sub_u32_e32 v3, 0, v2
	v_rcp_iflag_f32_e32 v4, v4
	v_add_u32_e32 v5, s2, v1
	v_mul_f32_e32 v4, 0x4f7ffffe, v4
	v_cvt_u32_f32_e32 v4, v4
	v_mul_lo_u32 v1, v3, v4
	v_mul_hi_u32 v1, v4, v1
	v_add_u32_e32 v1, v4, v1
	v_mul_hi_u32 v1, v5, v1
	v_mul_lo_u32 v3, v1, v2
	v_sub_u32_e32 v3, v5, v3
	v_add_u32_e32 v4, 1, v1
	v_cmp_ge_u32_e32 vcc, v3, v2
	s_nop 1
	v_cndmask_b32_e32 v1, v1, v4, vcc
	v_sub_u32_e32 v4, v3, v2
	v_cndmask_b32_e32 v3, v3, v4, vcc
	v_add_u32_e32 v4, 1, v1
	v_cmp_ge_u32_e32 vcc, v3, v2
	v_add_u32_e32 v3, 1, v5
	s_nop 0
	v_cndmask_b32_e32 v1, v1, v4, vcc
	v_mul_lo_u32 v4, v2, v1
	v_add_u32_e32 v2, v4, v2
	v_cmp_ne_u32_e32 vcc, v3, v2
	s_and_saveexec_b64 s[6:7], vcc
	s_xor_b64 s[6:7], exec, s[6:7]
	s_cbranch_execz .LBB0_887
	s_waitcnt lgkmcnt(0)
	s_cmp_lg_u32 s100, 0
	s_cbranch_scc1 .Lb3_wait
	s_cmpk_ge_u32 s3, 0x80
	s_cbranch_scc1 .Lb3_wait
	s_mov_b64 s[8:9], exec
	s_branch .LBB0_886
